# weight-prep phase: per-row gain loads and the 8 tile loads of a pass kept in flight together, gain multiply applied once after the pass barrier instead of a wait after every load
# speedup vs baseline: 1.0081x; 1.0015x over previous
; DI void prep_wt(const float* __restrict__ src, u16* __restrict__ dst, int K, int N, int Npad,
;                 const float* __restrict__ gain, float* tile) {
;     ...
;   for (int t0 = blockIdx.x; t0 < nt4; t0 += 4 * gridDim.x) {
;     f32x4 v[4][2];
; #pragma unroll
;     for (int j = 0; j < 4; ++j) {
;       const int t = t0 + j * gridDim.x;
;       const int kt = t % tk, nt = t / tk;
; #pragma unroll
;       for (int i = 0; i < 2; ++i) {
;         const int e = tid + NTHR * i; const int kk = e >> 4, n4 = (e & 15) * 4; const int n = nt * 64 + n4;
;         v[j][i] = (f32x4){0.f, 0.f, 0.f, 0.f};
;         if (t < nt4 && n < N) {
;           v[j][i] = *(const f32x4*)(src + (size_t)(kt * 64 + kk) * N + n);
;           if (gain) v[j][i] *= gain[kt * 64 + kk];
;         }
.LBB0_23:
	v_mov_b64 v[60:61], 0
	v_mov_b64 v[62:63], 0
	v_mov_b64 v[64:65], 0
	v_mov_b64 v[66:67], 0
	v_mov_b64 v[68:69], 0
	v_mov_b64 v[70:71], 0
	v_mov_b64 v[72:73], 0
	v_mov_b64 v[74:75], 0
	v_mov_b64 v[76:77], 0
	v_mov_b64 v[78:79], 0
	v_mov_b64 v[80:81], 0
	v_mov_b64 v[82:83], 0
	v_mov_b64 v[84:85], 0
	v_mov_b64 v[86:87], 0
	v_mov_b64 v[88:89], 0
	v_mov_b64 v[90:91], 0
	v_mov_b32_e32 v200, 1.0
	v_mov_b32_e32 v202, 1.0
	v_mov_b32_e32 v204, 1.0
	v_mov_b32_e32 v206, 1.0
	v_mov_b32_e32 v208, 1.0
	v_mov_b32_e32 v210, 1.0
	v_mov_b32_e32 v212, 1.0
	v_mov_b32_e32 v214, 1.0
	s_ashr_i32 s0, s65, 31
	s_lshr_b32 s0, s0, 28
	s_add_i32 s0, s65, s0
	s_ashr_i32 s2, s0, 4
	s_lshl_b32 s83, s2, 6
	v_or_b32_e32 v0, s83, v39
	s_lshl_b32 s2, s2, 10
	v_ashrrev_i32_e32 v1, 31, v0
	v_cmp_gt_i32_e64 s[0:1], s78, v0
	s_sub_i32 s84, 0, s2
	v_lshl_add_u64 v[8:9], v[0:1], 2, s[42:43]
	v_mov_b32_e32 v0, 0
	v_cmp_ne_u32_e64 s[2:3], 1, v38
	v_mov_b32_e32 v4, 0
	v_mov_b32_e32 v5, 0
	v_mov_b32_e32 v6, 0
	v_mov_b32_e32 v7, 0
	s_and_saveexec_b64 s[46:47], s[0:1]
	s_cbranch_execz .LBB0_26
	s_add_i32 s48, s84, s64
	v_add_u32_e32 v2, s48, v42
	v_mad_i64_i32 v[4:5], s[48:49], v2, s79, v[8:9]
	global_load_dwordx4 v[60:63], v[4:5], off
	s_and_b64 vcc, exec, s[2:3]
	s_cbranch_vccnz .LBB0_26
	v_ashrrev_i32_e32 v3, 31, v2
	v_lshl_add_u64 v[2:3], v[2:3], 2, s[40:41]
	global_load_dword v200, v[2:3], off
.LBB0_26:
	s_or_b64 exec, exec, s[46:47]
	v_mov_b32_e32 v1, 0
	v_mov_b32_e32 v2, 0
	v_mov_b32_e32 v3, 0
	s_and_saveexec_b64 s[46:47], s[0:1]
	s_cbranch_execz .LBB0_29
	s_add_i32 s0, s84, s64
	v_add_u32_e32 v10, s0, v43
	v_mad_i64_i32 v[0:1], s[0:1], v10, s79, v[8:9]
	global_load_dwordx4 v[64:67], v[0:1], off
	s_and_b64 vcc, exec, s[2:3]
	s_cbranch_vccnz .LBB0_29
	v_ashrrev_i32_e32 v11, 31, v10
	v_lshl_add_u64 v[8:9], v[10:11], 2, s[40:41]
	global_load_dword v202, v[8:9], off
.LBB0_29:
	s_or_b64 exec, exec, s[46:47]
	s_add_i32 s0, s60, s65
	s_ashr_i32 s1, s0, 31
	s_lshr_b32 s1, s1, 28
	s_add_i32 s1, s0, s1
	s_and_b32 s46, s1, 0x3fffff0
	s_lshl_b32 s1, s1, 2
	s_sub_i32 s50, s0, s46
	s_andn2_b32 s1, s1, 63
	v_or_b32_e32 v8, s1, v39
	s_cmpk_lt_i32 s0, 0x240
	s_cselect_b64 s[46:47], -1, 0
	v_cmp_gt_i32_e32 vcc, s78, v8
	v_ashrrev_i32_e32 v9, 31, v8
	s_and_b64 s[48:49], s[46:47], vcc
	s_lshl_b32 s0, s50, 6
	v_lshl_add_u64 v[16:17], v[8:9], 2, s[42:43]
	v_mov_b32_e32 v8, 0
	v_mov_b32_e32 v12, 0
	v_mov_b32_e32 v13, 0
	v_mov_b32_e32 v14, 0
	v_mov_b32_e32 v15, 0
	s_and_saveexec_b64 s[50:51], s[48:49]
	s_cbranch_execz .LBB0_32
	v_add_u32_e32 v10, s0, v42
	v_mad_i64_i32 v[12:13], s[52:53], v10, s79, v[16:17]
	global_load_dwordx4 v[68:71], v[12:13], off
	s_and_b64 vcc, exec, s[2:3]
	s_cbranch_vccnz .LBB0_32
	v_ashrrev_i32_e32 v11, 31, v10
	v_lshl_add_u64 v[10:11], v[10:11], 2, s[40:41]
	global_load_dword v204, v[10:11], off
.LBB0_32:
	s_or_b64 exec, exec, s[50:51]
	v_mov_b32_e32 v9, 0
	v_mov_b32_e32 v10, 0
	v_mov_b32_e32 v11, 0
	s_and_saveexec_b64 s[50:51], s[48:49]
	s_cbranch_execz .LBB0_35
	v_add_u32_e32 v18, s0, v43
	v_mad_i64_i32 v[8:9], s[48:49], v18, s79, v[16:17]
	global_load_dwordx4 v[72:75], v[8:9], off
	s_and_b64 vcc, exec, s[2:3]
	s_cbranch_vccnz .LBB0_35
	v_ashrrev_i32_e32 v19, 31, v18
	v_lshl_add_u64 v[16:17], v[18:19], 2, s[40:41]
	global_load_dword v206, v[16:17], off
.LBB0_35:
	s_or_b64 exec, exec, s[50:51]
	s_add_i32 s48, s63, s65
	s_ashr_i32 s49, s48, 31
	s_lshr_b32 s49, s49, 28
	s_add_i32 s49, s48, s49
	s_and_b32 s50, s49, 0x3fffff0
	s_lshl_b32 s49, s49, 2
	s_sub_i32 s54, s48, s50
	s_andn2_b32 s49, s49, 63
	v_or_b32_e32 v16, s49, v39
	s_cmpk_lt_i32 s48, 0x240
	s_cselect_b64 s[50:51], -1, 0
	v_cmp_gt_i32_e32 vcc, s78, v16
	v_ashrrev_i32_e32 v17, 31, v16
	s_and_b64 s[52:53], s[50:51], vcc
	s_lshl_b32 s48, s54, 6
	v_lshl_add_u64 v[24:25], v[16:17], 2, s[42:43]
	v_mov_b32_e32 v16, 0
	v_mov_b32_e32 v20, 0
	v_mov_b32_e32 v21, 0
	v_mov_b32_e32 v22, 0
	v_mov_b32_e32 v23, 0
	s_and_saveexec_b64 s[54:55], s[52:53]
	s_cbranch_execz .LBB0_38
	v_add_u32_e32 v18, s48, v42
	v_mad_i64_i32 v[20:21], s[56:57], v18, s79, v[24:25]
	global_load_dwordx4 v[76:79], v[20:21], off
	s_and_b64 vcc, exec, s[2:3]
	s_cbranch_vccnz .LBB0_38
	v_ashrrev_i32_e32 v19, 31, v18
	v_lshl_add_u64 v[18:19], v[18:19], 2, s[40:41]
	global_load_dword v208, v[18:19], off
.LBB0_38:
	s_or_b64 exec, exec, s[54:55]
	v_mov_b32_e32 v17, 0
	v_mov_b32_e32 v18, 0
	v_mov_b32_e32 v19, 0
	s_and_saveexec_b64 s[54:55], s[52:53]
	s_cbranch_execz .LBB0_41
	v_add_u32_e32 v26, s48, v43
	v_mad_i64_i32 v[16:17], s[52:53], v26, s79, v[24:25]
	global_load_dwordx4 v[80:83], v[16:17], off
	s_and_b64 vcc, exec, s[2:3]
	s_cbranch_vccnz .LBB0_41
	v_ashrrev_i32_e32 v27, 31, v26
	v_lshl_add_u64 v[24:25], v[26:27], 2, s[40:41]
	global_load_dword v210, v[24:25], off
; DI void prep_wt(const float* __restrict__ src, u16* __restrict__ dst, int K, int N, int Npad,
;                 const float* __restrict__ gain, float* tile) {
;     ...
;         const int e = tid + NTHR * i; const int kk = e >> 4, n4 = (e & 15) * 4; const int n = nt * 64 + n4;
;         v[j][i] = (f32x4){0.f, 0.f, 0.f, 0.f};
;         if (t < nt4 && n < N) {
;           v[j][i] = *(const f32x4*)(src + (size_t)(kt * 64 + kk) * N + n);
;           if (gain) v[j][i] *= gain[kt * 64 + kk];
;         }
;       }
;     }
;     __syncthreads();
; #pragma unroll
;     for (int j = 0; j < 4; ++j)
; #pragma unroll
;       for (int i = 0; i < 2; ++i) {
;         const int e = tid + NTHR * i; const int kk = e >> 4, n4 = (e & 15) * 4;
;         float* tp = tile + j * TS + kk * 65 + n4;
;         tp[0] = v[j][i][0]; tp[1] = v[j][i][1]; tp[2] = v[j][i][2]; tp[3] = v[j][i][3];
;       }
;     __syncthreads();
; #pragma unroll
;     for (int j = 0; j < 4; ++j) {
;       const int t = t0 + j * gridDim.x;
;       if (t < nt4) {
;         const int kt = t % tk, nt = t / tk;
;         const int nn = tid >> 3, k8 = (tid & 7) * 8;
;         const float* tp = tile + j * TS + k8 * 65 + nn;
;         u32x4 u;
;         u.x = pack2(tp[0 * 65], tp[1 * 65]); u.y = pack2(tp[2 * 65], tp[3 * 65]);
;         u.z = pack2(tp[4 * 65], tp[5 * 65]); u.w = pack2(tp[6 * 65], tp[7 * 65]);
;         *(u32x4*)(dst + (size_t)(nt * 64 + nn) * K + kt * 64 + k8) = u;
.LBB0_41:
	s_or_b64 exec, exec, s[54:55]
	s_mul_i32 s52, s60, 3
	s_add_i32 s52, s52, s65
	s_ashr_i32 s53, s52, 31
	s_lshr_b32 s53, s53, 28
	s_add_i32 s53, s52, s53
	s_and_b32 s54, s53, 0x3fffff0
	s_lshl_b32 s53, s53, 2
	s_sub_i32 s58, s52, s54
	s_andn2_b32 s53, s53, 63
	v_or_b32_e32 v24, s53, v39
	s_cmpk_lt_i32 s52, 0x240
	s_cselect_b64 s[54:55], -1, 0
	v_cmp_gt_i32_e32 vcc, s78, v24
	v_ashrrev_i32_e32 v25, 31, v24
	s_and_b64 s[56:57], s[54:55], vcc
	s_lshl_b32 s52, s58, 6
	v_lshl_add_u64 v[34:35], v[24:25], 2, s[42:43]
	v_mov_b32_e32 v24, 0
	v_mov_b32_e32 v28, 0
	v_mov_b32_e32 v29, 0
	v_mov_b32_e32 v30, 0
	v_mov_b32_e32 v31, 0
	s_and_saveexec_b64 s[58:59], s[56:57]
	s_cbranch_execz .LBB0_44
	v_add_u32_e32 v26, s52, v42
	v_mad_i64_i32 v[28:29], s[86:87], v26, s79, v[34:35]
	global_load_dwordx4 v[84:87], v[28:29], off
	s_and_b64 vcc, exec, s[2:3]
	s_cbranch_vccnz .LBB0_44
	v_ashrrev_i32_e32 v27, 31, v26
	v_lshl_add_u64 v[26:27], v[26:27], 2, s[40:41]
	global_load_dword v212, v[26:27], off
.LBB0_44:
	s_or_b64 exec, exec, s[58:59]
	v_mov_b32_e32 v25, 0
	v_mov_b32_e32 v26, 0
	v_mov_b32_e32 v27, 0
	s_and_saveexec_b64 s[58:59], s[56:57]
	s_cbranch_execz .LBB0_47
	v_add_u32_e32 v36, s52, v43
	v_mad_i64_i32 v[24:25], s[56:57], v36, s79, v[34:35]
	global_load_dwordx4 v[88:91], v[24:25], off
	s_and_b64 vcc, exec, s[2:3]
	s_cbranch_vccnz .LBB0_47
	v_ashrrev_i32_e32 v37, 31, v36
	v_lshl_add_u64 v[34:35], v[36:37], 2, s[40:41]
	global_load_dword v214, v[34:35], off
.LBB0_47:
	s_or_b64 exec, exec, s[58:59]
	s_barrier
	s_waitcnt vmcnt(0)
	v_pk_mul_f32 v[6:7], v[62:63], v[200:201] op_sel_hi:[1,0]
	v_pk_mul_f32 v[4:5], v[60:61], v[200:201] op_sel_hi:[1,0]
	v_pk_mul_f32 v[2:3], v[66:67], v[202:203] op_sel_hi:[1,0]
	v_pk_mul_f32 v[0:1], v[64:65], v[202:203] op_sel_hi:[1,0]
	v_pk_mul_f32 v[14:15], v[70:71], v[204:205] op_sel_hi:[1,0]
	v_pk_mul_f32 v[12:13], v[68:69], v[204:205] op_sel_hi:[1,0]
	v_pk_mul_f32 v[10:11], v[74:75], v[206:207] op_sel_hi:[1,0]
	v_pk_mul_f32 v[8:9], v[72:73], v[206:207] op_sel_hi:[1,0]
	v_pk_mul_f32 v[22:23], v[78:79], v[208:209] op_sel_hi:[1,0]
	v_pk_mul_f32 v[20:21], v[76:77], v[208:209] op_sel_hi:[1,0]
	v_pk_mul_f32 v[18:19], v[82:83], v[210:211] op_sel_hi:[1,0]
	v_pk_mul_f32 v[16:17], v[80:81], v[210:211] op_sel_hi:[1,0]
	v_pk_mul_f32 v[30:31], v[86:87], v[212:213] op_sel_hi:[1,0]
	v_pk_mul_f32 v[28:29], v[84:85], v[212:213] op_sel_hi:[1,0]
	v_pk_mul_f32 v[26:27], v[90:91], v[214:215] op_sel_hi:[1,0]
	v_pk_mul_f32 v[24:25], v[88:89], v[214:215] op_sel_hi:[1,0]
	ds_write2_b32 v44, v4, v5 offset1:1
	ds_write2_b32 v44, v6, v7 offset0:2 offset1:3
	ds_write2_b32 v45, v0, v1 offset1:1
	ds_write2_b32 v45, v2, v3 offset0:2 offset1:3
	v_add_u32_e32 v0, 0x4100, v44
	ds_write2_b32 v0, v12, v13 offset1:1
	v_add_u32_e32 v0, 0x4108, v44
	ds_write2_b32 v0, v14, v15 offset1:1
	v_add_u32_e32 v0, 0x4100, v45
	ds_write2_b32 v0, v8, v9 offset1:1
	v_add_u32_e32 v0, 0x4108, v45
	ds_write2_b32 v0, v10, v11 offset1:1
	v_add_u32_e32 v0, 0x8200, v44
	ds_write2_b32 v0, v20, v21 offset1:1
	v_add_u32_e32 v0, 0x8208, v44
	ds_write2_b32 v0, v22, v23 offset1:1
	v_add_u32_e32 v0, 0x8200, v45
	ds_write2_b32 v0, v16, v17 offset1:1
	v_add_u32_e32 v0, 0x8208, v45
	ds_write2_b32 v0, v18, v19 offset1:1
	v_add_u32_e32 v0, 0xc300, v44
	ds_write2_b32 v0, v28, v29 offset1:1
	v_add_u32_e32 v0, 0xc308, v44
	ds_write2_b32 v0, v30, v31 offset1:1
	v_add_u32_e32 v0, 0xc300, v45
	ds_write2_b32 v0, v24, v25 offset1:1
	v_add_u32_e32 v0, 0xc308, v45
	ds_write2_b32 v0, v26, v27 offset1:1
	s_waitcnt lgkmcnt(0)
	s_barrier
	ds_read2_b32 v[0:1], v41 offset1:65
	ds_read2_b32 v[2:3], v41 offset0:130 offset1:195
	v_add_u32_e32 v6, 0x400, v41
	ds_read2_b32 v[4:5], v6 offset0:4 offset1:69
	ds_read2_b32 v[6:7], v6 offset0:134 offset1:199
	s_add_i32 s2, s64, s84
	s_waitcnt lgkmcnt(3)
	v_cvt_pk_bf16_f32 v0, v0, v1
	s_waitcnt lgkmcnt(2)
	v_cvt_pk_bf16_f32 v1, v2, v3
	s_waitcnt lgkmcnt(1)
	v_cvt_pk_bf16_f32 v2, v4, v5
	v_add_u32_e32 v4, s83, v40
	v_ashrrev_i32_e32 v5, 31, v4
	v_lshlrev_b64 v[4:5], 11, v[4:5]
	v_lshl_add_u64 v[4:5], s[44:45], 0, v[4:5]
	s_ashr_i32 s3, s2, 31
	v_lshl_add_u64 v[4:5], s[2:3], 1, v[4:5]
	s_waitcnt lgkmcnt(0)
	v_cvt_pk_bf16_f32 v3, v6, v7
	v_lshl_add_u64 v[4:5], v[4:5], 0, v[32:33]
	s_andn2_b64 vcc, exec, s[46:47]
	global_store_dwordx4 v[4:5], v[0:3], off
	s_cbranch_vccz .LBB0_50
	s_andn2_b64 vcc, exec, s[50:51]
	s_cbranch_vccz .LBB0_51

; DI void prep_wt(const float* __restrict__ src, u16* __restrict__ dst, int K, int N, int Npad,
;                 const float* __restrict__ gain, float* tile) {
;     ...
;   for (int t0 = blockIdx.x; t0 < nt4; t0 += 4 * gridDim.x) {
;     f32x4 v[4][2];
; #pragma unroll
;     for (int j = 0; j < 4; ++j) {
;       const int t = t0 + j * gridDim.x;
;       const int kt = t % tk, nt = t / tk;
; #pragma unroll
;       for (int i = 0; i < 2; ++i) {
;         const int e = tid + NTHR * i; const int kk = e >> 4, n4 = (e & 15) * 4; const int n = nt * 64 + n4;
;         v[j][i] = (f32x4){0.f, 0.f, 0.f, 0.f};
;         if (t < nt4 && n < N) {
;           v[j][i] = *(const f32x4*)(src + (size_t)(kt * 64 + kk) * N + n);
;           if (gain) v[j][i] *= gain[kt * 64 + kk];
;         }
.LBB0_56:
	v_mov_b64 v[60:61], 0
	v_mov_b64 v[62:63], 0
	v_mov_b64 v[64:65], 0
	v_mov_b64 v[66:67], 0
	v_mov_b64 v[68:69], 0
	v_mov_b64 v[70:71], 0
	v_mov_b64 v[72:73], 0
	v_mov_b64 v[74:75], 0
	v_mov_b64 v[76:77], 0
	v_mov_b64 v[78:79], 0
	v_mov_b64 v[80:81], 0
	v_mov_b64 v[82:83], 0
	v_mov_b64 v[84:85], 0
	v_mov_b64 v[86:87], 0
	v_mov_b64 v[88:89], 0
	v_mov_b64 v[90:91], 0
	v_mov_b32_e32 v200, 1.0
	v_mov_b32_e32 v202, 1.0
	v_mov_b32_e32 v204, 1.0
	v_mov_b32_e32 v206, 1.0
	v_mov_b32_e32 v208, 1.0
	v_mov_b32_e32 v210, 1.0
	v_mov_b32_e32 v212, 1.0
	v_mov_b32_e32 v214, 1.0
	s_mul_hi_i32 s0, s84, 0x2aaaaaab
	s_lshr_b32 s1, s0, 31
	s_add_i32 s86, s0, s1
	s_lshl_b32 s85, s86, 6
	v_or_b32_e32 v0, s85, v39
	v_ashrrev_i32_e32 v1, 31, v0
	v_lshl_add_u64 v[8:9], v[0:1], 2, s[42:43]
	v_cndmask_b32_e64 v1, 0, 1, s[30:31]
	v_cmp_gt_i32_e64 s[0:1], s72, v0
	s_mulk_i32 s86, 0xfe80
	v_mov_b32_e32 v0, 0
	v_cmp_ne_u32_e64 s[2:3], 1, v1
	v_mov_b32_e32 v4, 0
	v_mov_b32_e32 v5, 0
	v_mov_b32_e32 v6, 0
	v_mov_b32_e32 v7, 0
	s_and_saveexec_b64 s[48:49], s[0:1]
	s_cbranch_execz .LBB0_59
	s_add_i32 s50, s86, s83
	v_add_u32_e32 v2, s50, v42
	v_mad_i64_i32 v[4:5], s[50:51], v2, s80, v[8:9]
	global_load_dwordx4 v[60:63], v[4:5], off
	s_and_b64 vcc, exec, s[2:3]
	s_cbranch_vccnz .LBB0_59
	v_ashrrev_i32_e32 v3, 31, v2
	v_lshl_add_u64 v[2:3], v[2:3], 2, s[46:47]
	global_load_dword v200, v[2:3], off
.LBB0_59:
	s_or_b64 exec, exec, s[48:49]
	v_mov_b32_e32 v1, 0
	v_mov_b32_e32 v2, 0
	v_mov_b32_e32 v3, 0
	s_and_saveexec_b64 s[48:49], s[0:1]
	s_cbranch_execz .LBB0_62
	s_add_i32 s0, s86, s83
	v_add_u32_e32 v10, s0, v43
	v_mad_i64_i32 v[0:1], s[0:1], v10, s80, v[8:9]
	global_load_dwordx4 v[64:67], v[0:1], off
	s_and_b64 vcc, exec, s[2:3]
	s_cbranch_vccnz .LBB0_62
	v_ashrrev_i32_e32 v11, 31, v10
	v_lshl_add_u64 v[8:9], v[10:11], 2, s[46:47]
	global_load_dword v202, v[8:9], off
.LBB0_62:
	s_or_b64 exec, exec, s[48:49]
	s_add_i32 s0, s62, s84
	s_mul_hi_i32 s1, s0, 0x2aaaaaab
	s_lshr_b32 s48, s1, 31
	s_add_i32 s1, s1, s48
	s_mul_i32 s48, s1, 6
	s_sub_i32 s52, s0, s48
	s_lshl_b32 s1, s1, 6
	v_or_b32_e32 v8, s1, v39
	s_cmpk_lt_i32 s0, 0x48
	s_cselect_b64 s[48:49], -1, 0
	v_cmp_gt_i32_e32 vcc, s72, v8
	v_ashrrev_i32_e32 v9, 31, v8
	s_and_b64 s[50:51], s[48:49], vcc
	s_lshl_b32 s0, s52, 6
	v_lshl_add_u64 v[16:17], v[8:9], 2, s[42:43]
	v_mov_b32_e32 v8, 0
	v_mov_b32_e32 v12, 0
	v_mov_b32_e32 v13, 0
	v_mov_b32_e32 v14, 0
	v_mov_b32_e32 v15, 0
	s_and_saveexec_b64 s[52:53], s[50:51]
	s_cbranch_execz .LBB0_65
	v_add_u32_e32 v10, s0, v42
	v_mad_i64_i32 v[12:13], s[54:55], v10, s80, v[16:17]
	global_load_dwordx4 v[68:71], v[12:13], off
	s_and_b64 vcc, exec, s[2:3]
	s_cbranch_vccnz .LBB0_65
	v_ashrrev_i32_e32 v11, 31, v10
	v_lshl_add_u64 v[10:11], v[10:11], 2, s[46:47]
	global_load_dword v204, v[10:11], off
.LBB0_65:
	s_or_b64 exec, exec, s[52:53]
	v_mov_b32_e32 v9, 0
	v_mov_b32_e32 v10, 0
	v_mov_b32_e32 v11, 0
	s_and_saveexec_b64 s[52:53], s[50:51]
	s_cbranch_execz .LBB0_68
	v_add_u32_e32 v18, s0, v43
	v_mad_i64_i32 v[8:9], s[50:51], v18, s80, v[16:17]
	global_load_dwordx4 v[72:75], v[8:9], off
	s_and_b64 vcc, exec, s[2:3]
	s_cbranch_vccnz .LBB0_68
	v_ashrrev_i32_e32 v19, 31, v18
	v_lshl_add_u64 v[16:17], v[18:19], 2, s[46:47]
	global_load_dword v206, v[16:17], off
.LBB0_68:
	s_or_b64 exec, exec, s[52:53]
	s_add_i32 s50, s65, s84
	s_mul_hi_i32 s51, s50, 0x2aaaaaab
	s_lshr_b32 s52, s51, 31
	s_add_i32 s51, s51, s52
	s_mul_i32 s52, s51, 6
	s_sub_i32 s56, s50, s52
	s_lshl_b32 s51, s51, 6
	v_or_b32_e32 v16, s51, v39
	s_cmpk_lt_i32 s50, 0x48
	s_cselect_b64 s[52:53], -1, 0
	v_cmp_gt_i32_e32 vcc, s72, v16
	v_ashrrev_i32_e32 v17, 31, v16
	s_and_b64 s[54:55], s[52:53], vcc
	s_lshl_b32 s50, s56, 6
	v_lshl_add_u64 v[24:25], v[16:17], 2, s[42:43]
	v_mov_b32_e32 v16, 0
	v_mov_b32_e32 v20, 0
	v_mov_b32_e32 v21, 0
	v_mov_b32_e32 v22, 0
	v_mov_b32_e32 v23, 0
	s_and_saveexec_b64 s[56:57], s[54:55]
	s_cbranch_execz .LBB0_71
	v_add_u32_e32 v18, s50, v42
	v_mad_i64_i32 v[20:21], s[58:59], v18, s80, v[24:25]
	global_load_dwordx4 v[76:79], v[20:21], off
	s_and_b64 vcc, exec, s[2:3]
	s_cbranch_vccnz .LBB0_71
	v_ashrrev_i32_e32 v19, 31, v18
	v_lshl_add_u64 v[18:19], v[18:19], 2, s[46:47]
	global_load_dword v208, v[18:19], off
.LBB0_71:
	s_or_b64 exec, exec, s[56:57]
	v_mov_b32_e32 v17, 0
	v_mov_b32_e32 v18, 0
	v_mov_b32_e32 v19, 0
	s_and_saveexec_b64 s[56:57], s[54:55]
	s_cbranch_execz .LBB0_74
	v_add_u32_e32 v26, s50, v43
	v_mad_i64_i32 v[16:17], s[54:55], v26, s80, v[24:25]
	global_load_dwordx4 v[80:83], v[16:17], off
	s_and_b64 vcc, exec, s[2:3]
	s_cbranch_vccnz .LBB0_74
	v_ashrrev_i32_e32 v27, 31, v26
	v_lshl_add_u64 v[24:25], v[26:27], 2, s[46:47]
	global_load_dword v210, v[24:25], off
; DI void prep_wt(const float* __restrict__ src, u16* __restrict__ dst, int K, int N, int Npad,
;                 const float* __restrict__ gain, float* tile) {
;     ...
;         const int e = tid + NTHR * i; const int kk = e >> 4, n4 = (e & 15) * 4; const int n = nt * 64 + n4;
;         v[j][i] = (f32x4){0.f, 0.f, 0.f, 0.f};
;         if (t < nt4 && n < N) {
;           v[j][i] = *(const f32x4*)(src + (size_t)(kt * 64 + kk) * N + n);
;           if (gain) v[j][i] *= gain[kt * 64 + kk];
;         }
;       }
;     }
;     __syncthreads();
; #pragma unroll
;     for (int j = 0; j < 4; ++j)
; #pragma unroll
;       for (int i = 0; i < 2; ++i) {
;         const int e = tid + NTHR * i; const int kk = e >> 4, n4 = (e & 15) * 4;
;         float* tp = tile + j * TS + kk * 65 + n4;
;         tp[0] = v[j][i][0]; tp[1] = v[j][i][1]; tp[2] = v[j][i][2]; tp[3] = v[j][i][3];
;       }
;     __syncthreads();
; #pragma unroll
;     for (int j = 0; j < 4; ++j) {
;       const int t = t0 + j * gridDim.x;
;       if (t < nt4) {
;         const int kt = t % tk, nt = t / tk;
;         const int nn = tid >> 3, k8 = (tid & 7) * 8;
;         const float* tp = tile + j * TS + k8 * 65 + nn;
;         u32x4 u;
;         u.x = pack2(tp[0 * 65], tp[1 * 65]); u.y = pack2(tp[2 * 65], tp[3 * 65]);
;         u.z = pack2(tp[4 * 65], tp[5 * 65]); u.w = pack2(tp[6 * 65], tp[7 * 65]);
;         *(u32x4*)(dst + (size_t)(nt * 64 + nn) * K + kt * 64 + k8) = u;
.LBB0_74:
	s_or_b64 exec, exec, s[56:57]
	s_mul_i32 s54, s62, 3
	s_add_i32 s54, s54, s84
	s_mul_hi_i32 s55, s54, 0x2aaaaaab
	s_lshr_b32 s56, s55, 31
	s_add_i32 s55, s55, s56
	s_mul_i32 s56, s55, 6
	s_sub_i32 s60, s54, s56
	s_lshl_b32 s55, s55, 6
	v_or_b32_e32 v24, s55, v39
	s_cmpk_lt_i32 s54, 0x48
	s_cselect_b64 s[56:57], -1, 0
	v_cmp_gt_i32_e32 vcc, s72, v24
	v_ashrrev_i32_e32 v25, 31, v24
	s_and_b64 s[58:59], s[56:57], vcc
	s_lshl_b32 s54, s60, 6
	v_lshl_add_u64 v[34:35], v[24:25], 2, s[42:43]
	v_mov_b32_e32 v24, 0
	v_mov_b32_e32 v28, 0
	v_mov_b32_e32 v29, 0
	v_mov_b32_e32 v30, 0
	v_mov_b32_e32 v31, 0
	s_and_saveexec_b64 s[60:61], s[58:59]
	s_cbranch_execz .LBB0_77
	v_add_u32_e32 v26, s54, v42
	v_mad_i64_i32 v[28:29], s[88:89], v26, s80, v[34:35]
	global_load_dwordx4 v[84:87], v[28:29], off
	s_and_b64 vcc, exec, s[2:3]
	s_cbranch_vccnz .LBB0_77
	v_ashrrev_i32_e32 v27, 31, v26
	v_lshl_add_u64 v[26:27], v[26:27], 2, s[46:47]
	global_load_dword v212, v[26:27], off
.LBB0_77:
	s_or_b64 exec, exec, s[60:61]
	v_mov_b32_e32 v25, 0
	v_mov_b32_e32 v26, 0
	v_mov_b32_e32 v27, 0
	s_and_saveexec_b64 s[60:61], s[58:59]
	s_cbranch_execz .LBB0_80
	v_add_u32_e32 v36, s54, v43
	v_mad_i64_i32 v[24:25], s[58:59], v36, s80, v[34:35]
	global_load_dwordx4 v[88:91], v[24:25], off
	s_and_b64 vcc, exec, s[2:3]
	s_cbranch_vccnz .LBB0_80
	v_ashrrev_i32_e32 v37, 31, v36
	v_lshl_add_u64 v[34:35], v[36:37], 2, s[46:47]
	global_load_dword v214, v[34:35], off
.LBB0_80:
	s_or_b64 exec, exec, s[60:61]
	s_barrier
	s_waitcnt vmcnt(0)
	v_pk_mul_f32 v[6:7], v[62:63], v[200:201] op_sel_hi:[1,0]
	v_pk_mul_f32 v[4:5], v[60:61], v[200:201] op_sel_hi:[1,0]
	v_pk_mul_f32 v[2:3], v[66:67], v[202:203] op_sel_hi:[1,0]
	v_pk_mul_f32 v[0:1], v[64:65], v[202:203] op_sel_hi:[1,0]
	v_pk_mul_f32 v[14:15], v[70:71], v[204:205] op_sel_hi:[1,0]
	v_pk_mul_f32 v[12:13], v[68:69], v[204:205] op_sel_hi:[1,0]
	v_pk_mul_f32 v[10:11], v[74:75], v[206:207] op_sel_hi:[1,0]
	v_pk_mul_f32 v[8:9], v[72:73], v[206:207] op_sel_hi:[1,0]
	v_pk_mul_f32 v[22:23], v[78:79], v[208:209] op_sel_hi:[1,0]
	v_pk_mul_f32 v[20:21], v[76:77], v[208:209] op_sel_hi:[1,0]
	v_pk_mul_f32 v[18:19], v[82:83], v[210:211] op_sel_hi:[1,0]
	v_pk_mul_f32 v[16:17], v[80:81], v[210:211] op_sel_hi:[1,0]
	v_pk_mul_f32 v[30:31], v[86:87], v[212:213] op_sel_hi:[1,0]
	v_pk_mul_f32 v[28:29], v[84:85], v[212:213] op_sel_hi:[1,0]
	v_pk_mul_f32 v[26:27], v[90:91], v[214:215] op_sel_hi:[1,0]
	v_pk_mul_f32 v[24:25], v[88:89], v[214:215] op_sel_hi:[1,0]
	ds_write2_b32 v44, v4, v5 offset1:1
	ds_write2_b32 v44, v6, v7 offset0:2 offset1:3
	ds_write2_b32 v45, v0, v1 offset1:1
	ds_write2_b32 v45, v2, v3 offset0:2 offset1:3
	v_add_u32_e32 v0, 0x4100, v44
	ds_write2_b32 v0, v12, v13 offset1:1
	v_add_u32_e32 v0, 0x4108, v44
	ds_write2_b32 v0, v14, v15 offset1:1
	v_add_u32_e32 v0, 0x4100, v45
	ds_write2_b32 v0, v8, v9 offset1:1
	v_add_u32_e32 v0, 0x4108, v45
	ds_write2_b32 v0, v10, v11 offset1:1
	v_add_u32_e32 v0, 0x8200, v44
	ds_write2_b32 v0, v20, v21 offset1:1
	v_add_u32_e32 v0, 0x8208, v44
	ds_write2_b32 v0, v22, v23 offset1:1
	v_add_u32_e32 v0, 0x8200, v45
	ds_write2_b32 v0, v16, v17 offset1:1
	v_add_u32_e32 v0, 0x8208, v45
	ds_write2_b32 v0, v18, v19 offset1:1
	v_add_u32_e32 v0, 0xc300, v44
	ds_write2_b32 v0, v28, v29 offset1:1
	v_add_u32_e32 v0, 0xc308, v44
	ds_write2_b32 v0, v30, v31 offset1:1
	v_add_u32_e32 v0, 0xc300, v45
	ds_write2_b32 v0, v24, v25 offset1:1
	v_add_u32_e32 v0, 0xc308, v45
	v_add_u32_e32 v6, 0x400, v41
	ds_write2_b32 v0, v26, v27 offset1:1
	s_waitcnt lgkmcnt(0)
	s_barrier
	ds_read2_b32 v[0:1], v41 offset1:65
	ds_read2_b32 v[2:3], v41 offset0:130 offset1:195
	ds_read2_b32 v[4:5], v6 offset0:4 offset1:69
	ds_read2_b32 v[6:7], v6 offset0:134 offset1:199
	s_add_i32 s2, s83, s86
	s_ashr_i32 s3, s2, 31
	s_waitcnt lgkmcnt(3)
	v_cvt_pk_bf16_f32 v0, v0, v1
	s_waitcnt lgkmcnt(2)
	v_cvt_pk_bf16_f32 v1, v2, v3
	s_waitcnt lgkmcnt(1)
	v_cvt_pk_bf16_f32 v2, v4, v5
	s_waitcnt lgkmcnt(0)
	v_cvt_pk_bf16_f32 v3, v6, v7
	v_add_u32_e32 v6, s85, v40
	v_mov_b64_e32 v[4:5], s[44:45]
	v_mad_i64_i32 v[4:5], s[58:59], v6, s72, v[4:5]
	v_lshl_add_u64 v[4:5], s[2:3], 1, v[4:5]
	v_lshl_add_u64 v[4:5], v[4:5], 0, v[32:33]
	s_andn2_b64 vcc, exec, s[48:49]
	global_store_dwordx4 v[4:5], v[0:3], off
	s_cbranch_vccz .LBB0_83
	s_andn2_b64 vcc, exec, s[52:53]
	s_cbranch_vccz .LBB0_84

; DI void prep_wt(const float* __restrict__ src, u16* __restrict__ dst, int K, int N, int Npad,
;                 const float* __restrict__ gain, float* tile) {
;     ...
;   for (int t0 = blockIdx.x; t0 < nt4; t0 += 4 * gridDim.x) {
;     f32x4 v[4][2];
; #pragma unroll
;     for (int j = 0; j < 4; ++j) {
;       const int t = t0 + j * gridDim.x;
;       const int kt = t % tk, nt = t / tk;
; #pragma unroll
;       for (int i = 0; i < 2; ++i) {
;         const int e = tid + NTHR * i; const int kk = e >> 4, n4 = (e & 15) * 4; const int n = nt * 64 + n4;
;         v[j][i] = (f32x4){0.f, 0.f, 0.f, 0.f};
;         if (t < nt4 && n < N) {
;           v[j][i] = *(const f32x4*)(src + (size_t)(kt * 64 + kk) * N + n);
;           if (gain) v[j][i] *= gain[kt * 64 + kk];
;         }
.LBB0_89:
	v_mov_b64 v[60:61], 0
	v_mov_b64 v[62:63], 0
	v_mov_b64 v[64:65], 0
	v_mov_b64 v[66:67], 0
	v_mov_b64 v[68:69], 0
	v_mov_b64 v[70:71], 0
	v_mov_b64 v[72:73], 0
	v_mov_b64 v[74:75], 0
	v_mov_b64 v[76:77], 0
	v_mov_b64 v[78:79], 0
	v_mov_b64 v[80:81], 0
	v_mov_b64 v[82:83], 0
	v_mov_b64 v[84:85], 0
	v_mov_b64 v[86:87], 0
	v_mov_b64 v[88:89], 0
	v_mov_b64 v[90:91], 0
	v_mov_b32_e32 v200, 1.0
	v_mov_b32_e32 v202, 1.0
	v_mov_b32_e32 v204, 1.0
	v_mov_b32_e32 v206, 1.0
	v_mov_b32_e32 v208, 1.0
	v_mov_b32_e32 v210, 1.0
	v_mov_b32_e32 v212, 1.0
	v_mov_b32_e32 v214, 1.0
	s_ashr_i32 s0, s54, 31
	s_lshr_b32 s0, s0, 30
	s_add_i32 s0, s54, s0
	s_lshl_b32 s51, s0, 4
	s_andn2_b32 s51, s51, 63
	v_or_b32_e32 v0, s51, v39
	s_and_b32 s1, s0, 0x3fffffc
	v_ashrrev_i32_e32 v1, 31, v0
	s_sub_i32 s2, s54, s1
	v_lshl_add_u64 v[8:9], v[0:1], 2, s[44:45]
	v_cndmask_b32_e64 v1, 0, 1, s[34:35]
	v_cmp_gt_i32_e64 s[0:1], s81, v0
	s_lshl_b32 s50, s2, 6
	v_mov_b32_e32 v0, 0
	v_cmp_ne_u32_e64 s[2:3], 1, v1
	v_mov_b32_e32 v4, 0
	v_mov_b32_e32 v5, 0
	v_mov_b32_e32 v6, 0
	v_mov_b32_e32 v7, 0
	s_and_saveexec_b64 s[52:53], s[0:1]
	s_cbranch_execz .LBB0_92
	v_add_u32_e32 v2, s50, v42
	v_ashrrev_i32_e32 v3, 31, v2
	v_lshlrev_b64 v[4:5], 12, v[2:3]
	v_lshl_add_u64 v[4:5], v[8:9], 0, v[4:5]
	global_load_dwordx4 v[60:63], v[4:5], off
	s_and_b64 vcc, exec, s[2:3]
	s_cbranch_vccnz .LBB0_92
	v_lshl_add_u64 v[2:3], v[2:3], 2, s[48:49]
	global_load_dword v200, v[2:3], off
.LBB0_92:
	s_or_b64 exec, exec, s[52:53]
	v_mov_b32_e32 v1, 0
	v_mov_b32_e32 v2, 0
	v_mov_b32_e32 v3, 0
	s_and_saveexec_b64 s[52:53], s[0:1]
	s_cbranch_execz .LBB0_95
	v_add_u32_e32 v10, s50, v43
	v_ashrrev_i32_e32 v11, 31, v10
	v_lshlrev_b64 v[0:1], 12, v[10:11]
	v_lshl_add_u64 v[0:1], v[8:9], 0, v[0:1]
	global_load_dwordx4 v[64:67], v[0:1], off
	s_and_b64 vcc, exec, s[2:3]
	s_cbranch_vccnz .LBB0_95
	v_lshl_add_u64 v[8:9], v[10:11], 2, s[48:49]
	global_load_dword v202, v[8:9], off
.LBB0_95:
	s_or_b64 exec, exec, s[52:53]
	s_add_i32 s58, s83, s54
	s_ashr_i32 s0, s58, 31
	s_lshr_b32 s0, s0, 30
	s_add_i32 s0, s58, s0
	s_and_b32 s1, s0, 0x3fffffc
	s_sub_i32 s56, s58, s1
	s_lshl_b32 s1, s0, 4
	s_andn2_b32 s1, s1, 63
	v_or_b32_e32 v8, s1, v39
	s_cmp_lt_i32 s58, 64
	s_cselect_b64 s[52:53], -1, 0
	v_cmp_gt_i32_e32 vcc, s81, v8
	v_ashrrev_i32_e32 v9, 31, v8
	s_and_b64 s[54:55], s[52:53], vcc
	s_lshl_b32 s0, s56, 6
	v_lshl_add_u64 v[16:17], v[8:9], 2, s[44:45]
	v_mov_b32_e32 v8, 0
	v_mov_b32_e32 v12, 0
	v_mov_b32_e32 v13, 0
	v_mov_b32_e32 v14, 0
	v_mov_b32_e32 v15, 0
	s_and_saveexec_b64 s[56:57], s[54:55]
	s_cbranch_execz .LBB0_98
	v_add_u32_e32 v10, s0, v42
	v_ashrrev_i32_e32 v11, 31, v10
	v_lshlrev_b64 v[12:13], 12, v[10:11]
	v_lshl_add_u64 v[12:13], v[16:17], 0, v[12:13]
	global_load_dwordx4 v[68:71], v[12:13], off
	s_and_b64 vcc, exec, s[2:3]
	s_cbranch_vccnz .LBB0_98
	v_lshl_add_u64 v[10:11], v[10:11], 2, s[48:49]
	global_load_dword v204, v[10:11], off
.LBB0_98:
	s_or_b64 exec, exec, s[56:57]
	v_mov_b32_e32 v9, 0
	v_mov_b32_e32 v10, 0
	v_mov_b32_e32 v11, 0
	s_and_saveexec_b64 s[56:57], s[54:55]
	s_cbranch_execz .LBB0_101
	v_add_u32_e32 v18, s0, v43
	v_ashrrev_i32_e32 v19, 31, v18
	v_lshlrev_b64 v[8:9], 12, v[18:19]
	v_lshl_add_u64 v[8:9], v[16:17], 0, v[8:9]
	global_load_dwordx4 v[72:75], v[8:9], off
	s_and_b64 vcc, exec, s[2:3]
	s_cbranch_vccnz .LBB0_101
	v_lshl_add_u64 v[16:17], v[18:19], 2, s[48:49]
	global_load_dword v206, v[16:17], off
.LBB0_101:
	s_or_b64 exec, exec, s[56:57]
	s_add_i32 s62, s83, s58
	s_ashr_i32 s54, s62, 31
	s_lshr_b32 s54, s54, 30
	s_add_i32 s54, s62, s54
	s_and_b32 s55, s54, 0x3fffffc
	s_sub_i32 s60, s62, s55
	s_lshl_b32 s55, s54, 4
	s_andn2_b32 s55, s55, 63
	v_or_b32_e32 v16, s55, v39
	s_cmp_lt_i32 s62, 64
	s_cselect_b64 s[56:57], -1, 0
	v_cmp_gt_i32_e32 vcc, s81, v16
	v_ashrrev_i32_e32 v17, 31, v16
	s_and_b64 s[58:59], s[56:57], vcc
	s_lshl_b32 s54, s60, 6
	v_lshl_add_u64 v[24:25], v[16:17], 2, s[44:45]
	v_mov_b32_e32 v16, 0
	v_mov_b32_e32 v20, 0
	v_mov_b32_e32 v21, 0
	v_mov_b32_e32 v22, 0
	v_mov_b32_e32 v23, 0
	s_and_saveexec_b64 s[60:61], s[58:59]
	s_cbranch_execz .LBB0_104
	v_add_u32_e32 v18, s54, v42
	v_ashrrev_i32_e32 v19, 31, v18
	v_lshlrev_b64 v[20:21], 12, v[18:19]
	v_lshl_add_u64 v[20:21], v[24:25], 0, v[20:21]
	global_load_dwordx4 v[76:79], v[20:21], off
	s_and_b64 vcc, exec, s[2:3]
	s_cbranch_vccnz .LBB0_104
	v_lshl_add_u64 v[18:19], v[18:19], 2, s[48:49]
	global_load_dword v208, v[18:19], off
; DI void prep_wt(const float* __restrict__ src, u16* __restrict__ dst, int K, int N, int Npad,
;                 const float* __restrict__ gain, float* tile) {
;     ...
;         const int e = tid + NTHR * i; const int kk = e >> 4, n4 = (e & 15) * 4; const int n = nt * 64 + n4;
;         v[j][i] = (f32x4){0.f, 0.f, 0.f, 0.f};
;         if (t < nt4 && n < N) {
;           v[j][i] = *(const f32x4*)(src + (size_t)(kt * 64 + kk) * N + n);
;           if (gain) v[j][i] *= gain[kt * 64 + kk];
;         }
;       }
;     }
;     __syncthreads();
; #pragma unroll
;     for (int j = 0; j < 4; ++j)
; #pragma unroll
;       for (int i = 0; i < 2; ++i) {
;         const int e = tid + NTHR * i; const int kk = e >> 4, n4 = (e & 15) * 4;
;         float* tp = tile + j * TS + kk * 65 + n4;
;         tp[0] = v[j][i][0]; tp[1] = v[j][i][1]; tp[2] = v[j][i][2]; tp[3] = v[j][i][3];
;       }
;     __syncthreads();
; #pragma unroll
;     for (int j = 0; j < 4; ++j) {
;       const int t = t0 + j * gridDim.x;
;       if (t < nt4) {
;         const int kt = t % tk, nt = t / tk;
;         const int nn = tid >> 3, k8 = (tid & 7) * 8;
;         const float* tp = tile + j * TS + k8 * 65 + nn;
;         u32x4 u;
;         u.x = pack2(tp[0 * 65], tp[1 * 65]); u.y = pack2(tp[2 * 65], tp[3 * 65]);
;         u.z = pack2(tp[4 * 65], tp[5 * 65]); u.w = pack2(tp[6 * 65], tp[7 * 65]);
;         *(u32x4*)(dst + (size_t)(nt * 64 + nn) * K + kt * 64 + k8) = u;
.LBB0_104:
	s_or_b64 exec, exec, s[60:61]
	v_mov_b32_e32 v17, 0
	v_mov_b32_e32 v18, 0
	v_mov_b32_e32 v19, 0
	s_and_saveexec_b64 s[60:61], s[58:59]
	s_cbranch_execz .LBB0_107
	v_add_u32_e32 v26, s54, v43
	v_ashrrev_i32_e32 v27, 31, v26
	v_lshlrev_b64 v[16:17], 12, v[26:27]
	v_lshl_add_u64 v[16:17], v[24:25], 0, v[16:17]
	global_load_dwordx4 v[80:83], v[16:17], off
	s_and_b64 vcc, exec, s[2:3]
	s_cbranch_vccnz .LBB0_107
	v_lshl_add_u64 v[24:25], v[26:27], 2, s[48:49]
	global_load_dword v210, v[24:25], off
.LBB0_107:
	s_or_b64 exec, exec, s[60:61]
	s_add_i32 s84, s83, s62
	s_ashr_i32 s58, s84, 31
	s_lshr_b32 s58, s58, 30
	s_add_i32 s58, s84, s58
	s_and_b32 s59, s58, 0x3fffffc
	s_sub_i32 s64, s84, s59
	s_lshl_b32 s59, s58, 4
	s_andn2_b32 s59, s59, 63
	v_or_b32_e32 v24, s59, v39
	s_cmp_lt_i32 s84, 64
	s_cselect_b64 s[60:61], -1, 0
	v_cmp_gt_i32_e32 vcc, s81, v24
	v_ashrrev_i32_e32 v25, 31, v24
	s_and_b64 s[62:63], s[60:61], vcc
	s_lshl_b32 s58, s64, 6
	v_lshl_add_u64 v[34:35], v[24:25], 2, s[44:45]
	v_mov_b32_e32 v24, 0
	v_mov_b32_e32 v28, 0
	v_mov_b32_e32 v29, 0
	v_mov_b32_e32 v30, 0
	v_mov_b32_e32 v31, 0
	s_and_saveexec_b64 s[64:65], s[62:63]
	s_cbranch_execz .LBB0_110
	v_add_u32_e32 v26, s58, v42
	v_ashrrev_i32_e32 v27, 31, v26
	v_lshlrev_b64 v[28:29], 12, v[26:27]
	v_lshl_add_u64 v[28:29], v[34:35], 0, v[28:29]
	global_load_dwordx4 v[84:87], v[28:29], off
	s_and_b64 vcc, exec, s[2:3]
	s_cbranch_vccnz .LBB0_110
	v_lshl_add_u64 v[26:27], v[26:27], 2, s[48:49]
	global_load_dword v212, v[26:27], off
.LBB0_110:
	s_or_b64 exec, exec, s[64:65]
	v_mov_b32_e32 v25, 0
	v_mov_b32_e32 v26, 0
	v_mov_b32_e32 v27, 0
	s_and_saveexec_b64 s[64:65], s[62:63]
	s_cbranch_execz .LBB0_113
	v_add_u32_e32 v36, s58, v43
	v_ashrrev_i32_e32 v37, 31, v36
	v_lshlrev_b64 v[24:25], 12, v[36:37]
	v_lshl_add_u64 v[24:25], v[34:35], 0, v[24:25]
	global_load_dwordx4 v[88:91], v[24:25], off
	s_and_b64 vcc, exec, s[2:3]
	s_cbranch_vccnz .LBB0_113
	v_lshl_add_u64 v[34:35], v[36:37], 2, s[48:49]
	global_load_dword v214, v[34:35], off
.LBB0_113:
	s_or_b64 exec, exec, s[64:65]
	s_barrier
	s_waitcnt vmcnt(0)
	v_pk_mul_f32 v[6:7], v[62:63], v[200:201] op_sel_hi:[1,0]
	v_pk_mul_f32 v[4:5], v[60:61], v[200:201] op_sel_hi:[1,0]
	v_pk_mul_f32 v[2:3], v[66:67], v[202:203] op_sel_hi:[1,0]
	v_pk_mul_f32 v[0:1], v[64:65], v[202:203] op_sel_hi:[1,0]
	v_pk_mul_f32 v[14:15], v[70:71], v[204:205] op_sel_hi:[1,0]
	v_pk_mul_f32 v[12:13], v[68:69], v[204:205] op_sel_hi:[1,0]
	v_pk_mul_f32 v[10:11], v[74:75], v[206:207] op_sel_hi:[1,0]
	v_pk_mul_f32 v[8:9], v[72:73], v[206:207] op_sel_hi:[1,0]
	v_pk_mul_f32 v[22:23], v[78:79], v[208:209] op_sel_hi:[1,0]
	v_pk_mul_f32 v[20:21], v[76:77], v[208:209] op_sel_hi:[1,0]
	v_pk_mul_f32 v[18:19], v[82:83], v[210:211] op_sel_hi:[1,0]
	v_pk_mul_f32 v[16:17], v[80:81], v[210:211] op_sel_hi:[1,0]
	v_pk_mul_f32 v[30:31], v[86:87], v[212:213] op_sel_hi:[1,0]
	v_pk_mul_f32 v[28:29], v[84:85], v[212:213] op_sel_hi:[1,0]
	v_pk_mul_f32 v[26:27], v[90:91], v[214:215] op_sel_hi:[1,0]
	v_pk_mul_f32 v[24:25], v[88:89], v[214:215] op_sel_hi:[1,0]
	ds_write2_b32 v44, v4, v5 offset1:1
	ds_write2_b32 v44, v6, v7 offset0:2 offset1:3
	ds_write2_b32 v45, v0, v1 offset1:1
	ds_write2_b32 v45, v2, v3 offset0:2 offset1:3
	v_add_u32_e32 v0, 0x4100, v44
	ds_write2_b32 v0, v12, v13 offset1:1
	v_add_u32_e32 v0, 0x4108, v44
	ds_write2_b32 v0, v14, v15 offset1:1
	v_add_u32_e32 v0, 0x4100, v45
	ds_write2_b32 v0, v8, v9 offset1:1
	v_add_u32_e32 v0, 0x4108, v45
	ds_write2_b32 v0, v10, v11 offset1:1
	v_add_u32_e32 v0, 0x8200, v44
	ds_write2_b32 v0, v20, v21 offset1:1
	v_add_u32_e32 v0, 0x8208, v44
	ds_write2_b32 v0, v22, v23 offset1:1
	v_add_u32_e32 v0, 0x8200, v45
	ds_write2_b32 v0, v16, v17 offset1:1
	v_add_u32_e32 v0, 0x8208, v45
	ds_write2_b32 v0, v18, v19 offset1:1
	v_add_u32_e32 v0, 0xc300, v44
	ds_write2_b32 v0, v28, v29 offset1:1
	v_add_u32_e32 v0, 0xc308, v44
	ds_write2_b32 v0, v30, v31 offset1:1
	v_add_u32_e32 v0, 0xc300, v45
	ds_write2_b32 v0, v24, v25 offset1:1
	v_add_u32_e32 v0, 0xc308, v45
	ds_write2_b32 v0, v26, v27 offset1:1
	s_waitcnt lgkmcnt(0)
	s_barrier
	ds_read2_b32 v[0:1], v41 offset1:65
	ds_read2_b32 v[2:3], v41 offset0:130 offset1:195
	v_add_u32_e32 v6, 0x400, v41
	ds_read2_b32 v[4:5], v6 offset0:4 offset1:69
	ds_read2_b32 v[6:7], v6 offset0:134 offset1:199
	s_andn2_b64 vcc, exec, s[52:53]
	s_waitcnt lgkmcnt(3)
	v_cvt_pk_bf16_f32 v0, v0, v1
	s_waitcnt lgkmcnt(2)
	v_cvt_pk_bf16_f32 v1, v2, v3
	s_waitcnt lgkmcnt(1)
	v_cvt_pk_bf16_f32 v2, v4, v5
	v_add_u32_e32 v4, s51, v40
	v_ashrrev_i32_e32 v5, 31, v4
	v_lshlrev_b64 v[4:5], 9, v[4:5]
	v_lshl_add_u64 v[4:5], s[46:47], 0, v[4:5]
	s_ashr_i32 s51, s50, 31
	v_lshl_add_u64 v[4:5], s[50:51], 1, v[4:5]
	s_waitcnt lgkmcnt(0)
	v_cvt_pk_bf16_f32 v3, v6, v7
	v_lshl_add_u64 v[4:5], v[4:5], 0, v[32:33]
	global_store_dwordx4 v[4:5], v[0:3], off
	s_cbranch_vccz .LBB0_116
	s_andn2_b64 vcc, exec, s[56:57]
	s_cbranch_vccz .LBB0_117

; DI void prep_wt(const float* __restrict__ src, u16* __restrict__ dst, int K, int N, int Npad,
;                 const float* __restrict__ gain, float* tile) {
;     ...
;   for (int t0 = blockIdx.x; t0 < nt4; t0 += 4 * gridDim.x) {
;     f32x4 v[4][2];
; #pragma unroll
;     for (int j = 0; j < 4; ++j) {
;       const int t = t0 + j * gridDim.x;
;       const int kt = t % tk, nt = t / tk;
; #pragma unroll
;       for (int i = 0; i < 2; ++i) {
;         const int e = tid + NTHR * i; const int kk = e >> 4, n4 = (e & 15) * 4; const int n = nt * 64 + n4;
;         v[j][i] = (f32x4){0.f, 0.f, 0.f, 0.f};
;         if (t < nt4 && n < N) {
;           v[j][i] = *(const f32x4*)(src + (size_t)(kt * 64 + kk) * N + n);
;           if (gain) v[j][i] *= gain[kt * 64 + kk];
;         }
.LBB0_147:
	v_mov_b64 v[60:61], 0
	v_mov_b64 v[62:63], 0
	v_mov_b64 v[64:65], 0
	v_mov_b64 v[66:67], 0
	v_mov_b64 v[68:69], 0
	v_mov_b64 v[70:71], 0
	v_mov_b64 v[72:73], 0
	v_mov_b64 v[74:75], 0
	v_mov_b64 v[76:77], 0
	v_mov_b64 v[78:79], 0
	v_mov_b64 v[80:81], 0
	v_mov_b64 v[82:83], 0
	v_mov_b64 v[84:85], 0
	v_mov_b64 v[86:87], 0
	v_mov_b64 v[88:89], 0
	v_mov_b64 v[90:91], 0
	v_mov_b32_e32 v200, 1.0
	v_mov_b32_e32 v202, 1.0
	v_mov_b32_e32 v204, 1.0
	v_mov_b32_e32 v206, 1.0
	v_mov_b32_e32 v208, 1.0
	v_mov_b32_e32 v210, 1.0
	v_mov_b32_e32 v212, 1.0
	v_mov_b32_e32 v214, 1.0
	s_ashr_i32 s46, s83, 31
	s_lshr_b32 s46, s46, 28
	s_add_i32 s46, s83, s46
	s_ashr_i32 s46, s46, 4
	s_lshl_b32 s84, s46, 6
	v_or_b32_e32 v0, s84, v36
	s_lshl_b32 s46, s46, 10
	v_ashrrev_i32_e32 v1, 31, v0
	v_cmp_gt_i32_e32 vcc, s80, v0
	s_sub_i32 s85, 0, s46
	v_lshl_add_u64 v[8:9], v[0:1], 2, s[0:1]
	v_mov_b32_e32 v0, 0
	v_mov_b32_e32 v4, 0
	v_mov_b32_e32 v5, 0
	v_mov_b32_e32 v2, 0
	v_mov_b32_e32 v3, 0
	s_and_saveexec_b64 s[46:47], vcc
	s_cbranch_execz .LBB0_149
	s_add_i32 s48, s85, s65
	v_add_u32_e32 v2, s48, v40
	v_ashrrev_i32_e32 v3, 31, v2
	v_mad_i64_i32 v[4:5], s[48:49], v2, s82, v[8:9]
	v_lshl_add_u64 v[2:3], v[2:3], 2, s[40:41]
	global_load_dwordx4 v[60:63], v[4:5], off
	s_nop 0
	global_load_dword v200, v[2:3], off
.LBB0_149:
	s_or_b64 exec, exec, s[46:47]
	v_mov_b32_e32 v1, 0
	v_mov_b32_e32 v6, 0
	v_mov_b32_e32 v7, 0
	s_and_saveexec_b64 s[46:47], vcc
	s_cbranch_execz .LBB0_151
	s_add_i32 s48, s85, s65
	v_add_u32_e32 v0, s48, v41
	v_ashrrev_i32_e32 v1, 31, v0
	v_mad_i64_i32 v[6:7], s[48:49], v0, s82, v[8:9]
	v_lshl_add_u64 v[0:1], v[0:1], 2, s[40:41]
	global_load_dwordx4 v[64:67], v[6:7], off
	s_nop 0
	global_load_dword v202, v[0:1], off
.LBB0_151:
	s_or_b64 exec, exec, s[46:47]
	s_add_i32 s46, s36, s83
	s_ashr_i32 s47, s46, 31
	s_lshr_b32 s47, s47, 28
	s_add_i32 s47, s46, s47
	s_and_b32 s48, s47, 0x3fffff0
	s_lshl_b32 s47, s47, 2
	s_sub_i32 s52, s46, s48
	s_andn2_b32 s47, s47, 63
	v_or_b32_e32 v8, s47, v36
	s_cmpk_lt_i32 s46, 0x300
	s_cselect_b64 s[48:49], -1, 0
	v_cmp_gt_i32_e32 vcc, s80, v8
	v_ashrrev_i32_e32 v9, 31, v8
	s_and_b64 s[50:51], s[48:49], vcc
	s_lshl_b32 s46, s52, 6
	v_lshl_add_u64 v[16:17], v[8:9], 2, s[0:1]
	v_mov_b32_e32 v8, 0
	v_mov_b32_e32 v12, 0
	v_mov_b32_e32 v13, 0
	v_mov_b32_e32 v10, 0
	v_mov_b32_e32 v11, 0
	s_and_saveexec_b64 s[52:53], s[50:51]
	s_cbranch_execz .LBB0_153
	v_add_u32_e32 v10, s46, v40
	v_ashrrev_i32_e32 v11, 31, v10
	v_mad_i64_i32 v[12:13], s[54:55], v10, s82, v[16:17]
	v_lshl_add_u64 v[10:11], v[10:11], 2, s[40:41]
	global_load_dwordx4 v[68:71], v[12:13], off
	s_nop 0
	global_load_dword v204, v[10:11], off
.LBB0_153:
	s_or_b64 exec, exec, s[52:53]
	v_mov_b32_e32 v9, 0
	v_mov_b32_e32 v14, 0
	v_mov_b32_e32 v15, 0
	s_and_saveexec_b64 s[52:53], s[50:51]
	s_cbranch_execz .LBB0_155
	v_add_u32_e32 v8, s46, v41
	v_ashrrev_i32_e32 v9, 31, v8
	v_mad_i64_i32 v[14:15], s[50:51], v8, s82, v[16:17]
	v_lshl_add_u64 v[8:9], v[8:9], 2, s[40:41]
	global_load_dwordx4 v[72:75], v[14:15], off
	s_nop 0
	global_load_dword v206, v[8:9], off
.LBB0_155:
	s_or_b64 exec, exec, s[52:53]
	s_add_i32 s50, s64, s83
	s_ashr_i32 s51, s50, 31
	s_lshr_b32 s51, s51, 28
	s_add_i32 s51, s50, s51
	s_and_b32 s52, s51, 0x3fffff0
	s_lshl_b32 s51, s51, 2
	s_sub_i32 s56, s50, s52
	s_andn2_b32 s51, s51, 63
	v_or_b32_e32 v16, s51, v36
	s_cmpk_lt_i32 s50, 0x300
	s_cselect_b64 s[52:53], -1, 0
	v_cmp_gt_i32_e32 vcc, s80, v16
	v_ashrrev_i32_e32 v17, 31, v16
	s_and_b64 s[54:55], s[52:53], vcc
	s_lshl_b32 s50, s56, 6
	v_lshl_add_u64 v[24:25], v[16:17], 2, s[0:1]
	v_mov_b32_e32 v16, 0
	v_mov_b32_e32 v20, 0
	v_mov_b32_e32 v21, 0
	v_mov_b32_e32 v18, 0
	v_mov_b32_e32 v19, 0
	s_and_saveexec_b64 s[56:57], s[54:55]
	s_cbranch_execz .LBB0_157
	v_add_u32_e32 v18, s50, v40
	v_ashrrev_i32_e32 v19, 31, v18
	v_mad_i64_i32 v[20:21], s[58:59], v18, s82, v[24:25]
	v_lshl_add_u64 v[18:19], v[18:19], 2, s[40:41]
	global_load_dwordx4 v[76:79], v[20:21], off
	s_nop 0
	global_load_dword v208, v[18:19], off
.LBB0_157:
	s_or_b64 exec, exec, s[56:57]
	v_mov_b32_e32 v17, 0
	v_mov_b32_e32 v22, 0
	v_mov_b32_e32 v23, 0
	s_and_saveexec_b64 s[56:57], s[54:55]
	s_cbranch_execz .LBB0_159
	v_add_u32_e32 v16, s50, v41
	v_ashrrev_i32_e32 v17, 31, v16
	v_mad_i64_i32 v[22:23], s[54:55], v16, s82, v[24:25]
	v_lshl_add_u64 v[16:17], v[16:17], 2, s[40:41]
	global_load_dwordx4 v[80:83], v[22:23], off
	s_nop 0
	global_load_dword v210, v[16:17], off
; DI void prep_wt(const float* __restrict__ src, u16* __restrict__ dst, int K, int N, int Npad,
;                 const float* __restrict__ gain, float* tile) {
;     ...
;         const int e = tid + NTHR * i; const int kk = e >> 4, n4 = (e & 15) * 4; const int n = nt * 64 + n4;
;         v[j][i] = (f32x4){0.f, 0.f, 0.f, 0.f};
;         if (t < nt4 && n < N) {
;           v[j][i] = *(const f32x4*)(src + (size_t)(kt * 64 + kk) * N + n);
;           if (gain) v[j][i] *= gain[kt * 64 + kk];
;         }
;       }
;     }
;     __syncthreads();
; #pragma unroll
;     for (int j = 0; j < 4; ++j)
; #pragma unroll
;       for (int i = 0; i < 2; ++i) {
;         const int e = tid + NTHR * i; const int kk = e >> 4, n4 = (e & 15) * 4;
;         float* tp = tile + j * TS + kk * 65 + n4;
;         tp[0] = v[j][i][0]; tp[1] = v[j][i][1]; tp[2] = v[j][i][2]; tp[3] = v[j][i][3];
;       }
;     __syncthreads();
; #pragma unroll
;     for (int j = 0; j < 4; ++j) {
;       const int t = t0 + j * gridDim.x;
;       if (t < nt4) {
;         const int kt = t % tk, nt = t / tk;
;         const int nn = tid >> 3, k8 = (tid & 7) * 8;
;         const float* tp = tile + j * TS + k8 * 65 + nn;
;         u32x4 u;
;         u.x = pack2(tp[0 * 65], tp[1 * 65]); u.y = pack2(tp[2 * 65], tp[3 * 65]);
;         u.z = pack2(tp[4 * 65], tp[5 * 65]); u.w = pack2(tp[6 * 65], tp[7 * 65]);
;         *(u32x4*)(dst + (size_t)(nt * 64 + nn) * K + kt * 64 + k8) = u;
.LBB0_159:
	s_or_b64 exec, exec, s[56:57]
	s_mul_i32 s54, s36, 3
	s_add_i32 s54, s54, s83
	s_ashr_i32 s55, s54, 31
	s_lshr_b32 s55, s55, 28
	s_add_i32 s55, s54, s55
	s_and_b32 s56, s55, 0x3fffff0
	s_lshl_b32 s55, s55, 2
	s_sub_i32 s60, s54, s56
	s_andn2_b32 s55, s55, 63
	v_or_b32_e32 v24, s55, v36
	s_cmpk_lt_i32 s54, 0x300
	s_cselect_b64 s[56:57], -1, 0
	v_cmp_gt_i32_e32 vcc, s80, v24
	v_ashrrev_i32_e32 v25, 31, v24
	s_and_b64 s[58:59], s[56:57], vcc
	s_lshl_b32 s54, s60, 6
	v_lshl_add_u64 v[34:35], v[24:25], 2, s[0:1]
	v_mov_b32_e32 v24, 0
	v_mov_b32_e32 v28, 0
	v_mov_b32_e32 v29, 0
	v_mov_b32_e32 v26, 0
	v_mov_b32_e32 v27, 0
	s_and_saveexec_b64 s[60:61], s[58:59]
	s_cbranch_execz .LBB0_161
	v_add_u32_e32 v26, s54, v40
	v_ashrrev_i32_e32 v27, 31, v26
	v_mad_i64_i32 v[28:29], s[86:87], v26, s82, v[34:35]
	v_lshl_add_u64 v[26:27], v[26:27], 2, s[40:41]
	global_load_dwordx4 v[84:87], v[28:29], off
	s_nop 0
	global_load_dword v212, v[26:27], off
.LBB0_161:
	s_or_b64 exec, exec, s[60:61]
	v_mov_b32_e32 v25, 0
	v_mov_b32_e32 v30, 0
	v_mov_b32_e32 v31, 0
	s_and_saveexec_b64 s[60:61], s[58:59]
	s_cbranch_execz .LBB0_163
	v_add_u32_e32 v24, s54, v41
	v_ashrrev_i32_e32 v25, 31, v24
	v_mad_i64_i32 v[30:31], s[58:59], v24, s82, v[34:35]
	v_lshl_add_u64 v[24:25], v[24:25], 2, s[40:41]
	global_load_dwordx4 v[88:91], v[30:31], off
	s_nop 0
	global_load_dword v214, v[24:25], off
.LBB0_163:
	s_or_b64 exec, exec, s[60:61]
	s_barrier
	s_waitcnt vmcnt(0)
	v_pk_mul_f32 v[2:3], v[62:63], v[200:201] op_sel_hi:[1,0]
	v_pk_mul_f32 v[4:5], v[60:61], v[200:201] op_sel_hi:[1,0]
	v_pk_mul_f32 v[6:7], v[66:67], v[202:203] op_sel_hi:[1,0]
	v_pk_mul_f32 v[0:1], v[64:65], v[202:203] op_sel_hi:[1,0]
	v_pk_mul_f32 v[10:11], v[70:71], v[204:205] op_sel_hi:[1,0]
	v_pk_mul_f32 v[12:13], v[68:69], v[204:205] op_sel_hi:[1,0]
	v_pk_mul_f32 v[14:15], v[74:75], v[206:207] op_sel_hi:[1,0]
	v_pk_mul_f32 v[8:9], v[72:73], v[206:207] op_sel_hi:[1,0]
	v_pk_mul_f32 v[18:19], v[78:79], v[208:209] op_sel_hi:[1,0]
	v_pk_mul_f32 v[20:21], v[76:77], v[208:209] op_sel_hi:[1,0]
	v_pk_mul_f32 v[22:23], v[82:83], v[210:211] op_sel_hi:[1,0]
	v_pk_mul_f32 v[16:17], v[80:81], v[210:211] op_sel_hi:[1,0]
	v_pk_mul_f32 v[26:27], v[86:87], v[212:213] op_sel_hi:[1,0]
	v_pk_mul_f32 v[28:29], v[84:85], v[212:213] op_sel_hi:[1,0]
	v_pk_mul_f32 v[30:31], v[90:91], v[214:215] op_sel_hi:[1,0]
	v_pk_mul_f32 v[24:25], v[88:89], v[214:215] op_sel_hi:[1,0]
	ds_write2_b32 v42, v4, v5 offset1:1
	ds_write2_b32 v42, v2, v3 offset0:2 offset1:3
	ds_write2_b32 v43, v0, v1 offset1:1
	ds_write2_b32 v43, v6, v7 offset0:2 offset1:3
	v_add_u32_e32 v0, 0x4100, v42
	ds_write2_b32 v0, v12, v13 offset1:1
	v_add_u32_e32 v0, 0x4108, v42
	ds_write2_b32 v0, v10, v11 offset1:1
	v_add_u32_e32 v0, 0x4100, v43
	ds_write2_b32 v0, v8, v9 offset1:1
	v_add_u32_e32 v0, 0x4108, v43
	ds_write2_b32 v0, v14, v15 offset1:1
	v_add_u32_e32 v0, 0x8200, v42
	ds_write2_b32 v0, v20, v21 offset1:1
	v_add_u32_e32 v0, 0x8208, v42
	ds_write2_b32 v0, v18, v19 offset1:1
	v_add_u32_e32 v0, 0x8200, v43
	ds_write2_b32 v0, v16, v17 offset1:1
	v_add_u32_e32 v0, 0x8208, v43
	ds_write2_b32 v0, v22, v23 offset1:1
	v_add_u32_e32 v0, 0xc300, v42
	ds_write2_b32 v0, v28, v29 offset1:1
	v_add_u32_e32 v0, 0xc308, v42
	ds_write2_b32 v0, v26, v27 offset1:1
	v_add_u32_e32 v0, 0xc300, v43
	ds_write2_b32 v0, v24, v25 offset1:1
	v_add_u32_e32 v0, 0xc308, v43
	ds_write2_b32 v0, v30, v31 offset1:1
	s_waitcnt lgkmcnt(0)
	s_barrier
	ds_read2_b32 v[0:1], v39 offset1:65
	ds_read2_b32 v[2:3], v39 offset0:130 offset1:195
	v_add_u32_e32 v6, 0x400, v39
	ds_read2_b32 v[4:5], v6 offset0:4 offset1:69
	ds_read2_b32 v[6:7], v6 offset0:134 offset1:199
	s_add_i32 s58, s65, s85
	s_waitcnt lgkmcnt(3)
	v_cvt_pk_bf16_f32 v0, v0, v1
	s_waitcnt lgkmcnt(2)
	v_cvt_pk_bf16_f32 v1, v2, v3
	s_waitcnt lgkmcnt(1)
	v_cvt_pk_bf16_f32 v2, v4, v5
	v_add_u32_e32 v4, s84, v37
	v_ashrrev_i32_e32 v5, 31, v4
	v_lshlrev_b64 v[4:5], 11, v[4:5]
	v_lshl_add_u64 v[4:5], s[44:45], 0, v[4:5]
	s_ashr_i32 s59, s58, 31
	v_lshl_add_u64 v[4:5], s[58:59], 1, v[4:5]
	s_waitcnt lgkmcnt(0)
	v_cvt_pk_bf16_f32 v3, v6, v7
	v_lshl_add_u64 v[4:5], v[4:5], 0, v[32:33]
	s_andn2_b64 vcc, exec, s[48:49]
	global_store_dwordx4 v[4:5], v[0:3], off
	s_cbranch_vccz .LBB0_166
	s_andn2_b64 vcc, exec, s[52:53]
	s_cbranch_vccz .LBB0_167

; DI void prep_wt(const float* __restrict__ src, u16* __restrict__ dst, int K, int N, int Npad,
;                 const float* __restrict__ gain, float* tile) {
;     ...
;   for (int t0 = blockIdx.x; t0 < nt4; t0 += 4 * gridDim.x) {
;     f32x4 v[4][2];
; #pragma unroll
;     for (int j = 0; j < 4; ++j) {
;       const int t = t0 + j * gridDim.x;
;       const int kt = t % tk, nt = t / tk;
; #pragma unroll
;       for (int i = 0; i < 2; ++i) {
;         const int e = tid + NTHR * i; const int kk = e >> 4, n4 = (e & 15) * 4; const int n = nt * 64 + n4;
;         v[j][i] = (f32x4){0.f, 0.f, 0.f, 0.f};
;         if (t < nt4 && n < N) {
;           v[j][i] = *(const f32x4*)(src + (size_t)(kt * 64 + kk) * N + n);
;           if (gain) v[j][i] *= gain[kt * 64 + kk];
;         }
.LBB0_199:
	v_mov_b64 v[60:61], 0
	v_mov_b64 v[62:63], 0
	v_mov_b64 v[64:65], 0
	v_mov_b64 v[66:67], 0
	v_mov_b64 v[68:69], 0
	v_mov_b64 v[70:71], 0
	v_mov_b64 v[72:73], 0
	v_mov_b64 v[74:75], 0
	v_mov_b64 v[76:77], 0
	v_mov_b64 v[78:79], 0
	v_mov_b64 v[80:81], 0
	v_mov_b64 v[82:83], 0
	v_mov_b64 v[84:85], 0
	v_mov_b64 v[86:87], 0
	v_mov_b64 v[88:89], 0
	v_mov_b64 v[90:91], 0
	v_mov_b32_e32 v200, 1.0
	v_mov_b32_e32 v202, 1.0
	v_mov_b32_e32 v204, 1.0
	v_mov_b32_e32 v206, 1.0
	v_mov_b32_e32 v208, 1.0
	v_mov_b32_e32 v210, 1.0
	v_mov_b32_e32 v212, 1.0
	v_mov_b32_e32 v214, 1.0
	s_ashr_i32 s0, s34, 31
	s_lshr_b32 s0, s0, 28
	s_add_i32 s0, s34, s0
	s_lshl_b32 s29, s0, 2
	s_andn2_b32 s29, s29, 63
	s_and_b32 s1, s0, 0x3fffff0
	v_or_b32_e32 v0, s29, v38
	s_sub_i32 s28, s34, s1
	v_ashrrev_i32_e32 v1, 31, v0
	v_cmp_gt_i32_e64 s[0:1], s50, v0
	s_lshl_b32 s28, s28, 6
	v_lshl_add_u64 v[8:9], v[0:1], 2, s[8:9]
	v_mov_b32_e32 v0, 0
	v_mov_b32_e32 v4, 0
	v_mov_b32_e32 v5, 0
	v_mov_b32_e32 v6, 0
	v_mov_b32_e32 v7, 0
	s_and_saveexec_b64 s[30:31], s[0:1]
	s_cbranch_execz .LBB0_202
	v_add_u32_e32 v2, s28, v41
	v_ashrrev_i32_e32 v3, 31, v2
	v_lshlrev_b64 v[4:5], 14, v[2:3]
	v_lshl_add_u64 v[4:5], v[8:9], 0, v[4:5]
	global_load_dwordx4 v[60:63], v[4:5], off
	s_and_b64 vcc, exec, s[4:5]
	s_cbranch_vccnz .LBB0_202
	v_lshl_add_u64 v[2:3], v[2:3], 2, s[22:23]
	global_load_dword v200, v[2:3], off
.LBB0_202:
	s_or_b64 exec, exec, s[30:31]
	v_mov_b32_e32 v1, 0
	v_mov_b32_e32 v2, 0
	v_mov_b32_e32 v3, 0
	s_and_saveexec_b64 s[30:31], s[0:1]
	s_cbranch_execz .LBB0_205
	v_add_u32_e32 v10, s28, v42
	v_ashrrev_i32_e32 v11, 31, v10
	v_lshlrev_b64 v[0:1], 14, v[10:11]
	v_lshl_add_u64 v[0:1], v[8:9], 0, v[0:1]
	global_load_dwordx4 v[64:67], v[0:1], off
	s_and_b64 vcc, exec, s[4:5]
	s_cbranch_vccnz .LBB0_205
	v_lshl_add_u64 v[8:9], v[10:11], 2, s[22:23]
	global_load_dword v202, v[8:9], off
.LBB0_205:
	s_or_b64 exec, exec, s[30:31]
	s_add_i32 s38, s52, s34
	s_ashr_i32 s0, s38, 31
	s_lshr_b32 s0, s0, 28
	s_add_i32 s0, s38, s0
	s_and_b32 s1, s0, 0x3fffff0
	s_sub_i32 s36, s38, s1
	s_lshl_b32 s1, s0, 2
	s_andn2_b32 s1, s1, 63
	v_or_b32_e32 v8, s1, v38
	s_cmpk_lt_i32 s38, 0x400
	s_cselect_b64 s[30:31], -1, 0
	v_cmp_gt_i32_e32 vcc, s50, v8
	v_ashrrev_i32_e32 v9, 31, v8
	s_and_b64 s[34:35], s[30:31], vcc
	s_lshl_b32 s0, s36, 6
	v_lshl_add_u64 v[16:17], v[8:9], 2, s[8:9]
	v_mov_b32_e32 v8, 0
	v_mov_b32_e32 v12, 0
	v_mov_b32_e32 v13, 0
	v_mov_b32_e32 v14, 0
	v_mov_b32_e32 v15, 0
	s_and_saveexec_b64 s[36:37], s[34:35]
	s_cbranch_execz .LBB0_208
	v_add_u32_e32 v10, s0, v41
	v_ashrrev_i32_e32 v11, 31, v10
	v_lshlrev_b64 v[12:13], 14, v[10:11]
	v_lshl_add_u64 v[12:13], v[16:17], 0, v[12:13]
	global_load_dwordx4 v[68:71], v[12:13], off
	s_and_b64 vcc, exec, s[4:5]
	s_cbranch_vccnz .LBB0_208
	v_lshl_add_u64 v[10:11], v[10:11], 2, s[22:23]
	global_load_dword v204, v[10:11], off
.LBB0_208:
	s_or_b64 exec, exec, s[36:37]
	v_mov_b32_e32 v9, 0
	v_mov_b32_e32 v10, 0
	v_mov_b32_e32 v11, 0
	s_and_saveexec_b64 s[36:37], s[34:35]
	s_cbranch_execz .LBB0_211
	v_add_u32_e32 v18, s0, v42
	v_ashrrev_i32_e32 v19, 31, v18
	v_lshlrev_b64 v[8:9], 14, v[18:19]
	v_lshl_add_u64 v[8:9], v[16:17], 0, v[8:9]
	global_load_dwordx4 v[72:75], v[8:9], off
	s_and_b64 vcc, exec, s[4:5]
	s_cbranch_vccnz .LBB0_211
	v_lshl_add_u64 v[16:17], v[18:19], 2, s[22:23]
	global_load_dword v206, v[16:17], off
.LBB0_211:
	s_or_b64 exec, exec, s[36:37]
	s_add_i32 s42, s52, s38
	s_ashr_i32 s34, s42, 31
	s_lshr_b32 s34, s34, 28
	s_add_i32 s34, s42, s34
	s_and_b32 s35, s34, 0x3fffff0
	s_sub_i32 s40, s42, s35
	s_lshl_b32 s35, s34, 2
	s_andn2_b32 s35, s35, 63
	v_or_b32_e32 v16, s35, v38
	s_cmpk_lt_i32 s42, 0x400
	s_cselect_b64 s[36:37], -1, 0
	v_cmp_gt_i32_e32 vcc, s50, v16
	v_ashrrev_i32_e32 v17, 31, v16
	s_and_b64 s[38:39], s[36:37], vcc
	s_lshl_b32 s34, s40, 6
	v_lshl_add_u64 v[24:25], v[16:17], 2, s[8:9]
	v_mov_b32_e32 v16, 0
	v_mov_b32_e32 v20, 0
	v_mov_b32_e32 v21, 0
	v_mov_b32_e32 v22, 0
	v_mov_b32_e32 v23, 0
	s_and_saveexec_b64 s[40:41], s[38:39]
	s_cbranch_execz .LBB0_214
	v_add_u32_e32 v18, s34, v41
	v_ashrrev_i32_e32 v19, 31, v18
	v_lshlrev_b64 v[20:21], 14, v[18:19]
	v_lshl_add_u64 v[20:21], v[24:25], 0, v[20:21]
	global_load_dwordx4 v[76:79], v[20:21], off
	s_and_b64 vcc, exec, s[4:5]
	s_cbranch_vccnz .LBB0_214
	v_lshl_add_u64 v[18:19], v[18:19], 2, s[22:23]
	global_load_dword v208, v[18:19], off
.LBB0_214:
	s_or_b64 exec, exec, s[40:41]
	v_mov_b32_e32 v17, 0
	v_mov_b32_e32 v18, 0
	v_mov_b32_e32 v19, 0
	s_and_saveexec_b64 s[40:41], s[38:39]
	s_cbranch_execz .LBB0_217
	v_add_u32_e32 v26, s34, v42
	v_ashrrev_i32_e32 v27, 31, v26
	v_lshlrev_b64 v[16:17], 14, v[26:27]
	v_lshl_add_u64 v[16:17], v[24:25], 0, v[16:17]
	global_load_dwordx4 v[80:83], v[16:17], off
	s_and_b64 vcc, exec, s[4:5]
	s_cbranch_vccnz .LBB0_217
	v_lshl_add_u64 v[24:25], v[26:27], 2, s[22:23]
	global_load_dword v210, v[24:25], off
; DI void prep_wt(const float* __restrict__ src, u16* __restrict__ dst, int K, int N, int Npad,
;                 const float* __restrict__ gain, float* tile) {
;     ...
;         const int e = tid + NTHR * i; const int kk = e >> 4, n4 = (e & 15) * 4; const int n = nt * 64 + n4;
;         v[j][i] = (f32x4){0.f, 0.f, 0.f, 0.f};
;         if (t < nt4 && n < N) {
;           v[j][i] = *(const f32x4*)(src + (size_t)(kt * 64 + kk) * N + n);
;           if (gain) v[j][i] *= gain[kt * 64 + kk];
;         }
;       }
;     }
;     __syncthreads();
; #pragma unroll
;     for (int j = 0; j < 4; ++j)
; #pragma unroll
;       for (int i = 0; i < 2; ++i) {
;         const int e = tid + NTHR * i; const int kk = e >> 4, n4 = (e & 15) * 4;
;         float* tp = tile + j * TS + kk * 65 + n4;
;         tp[0] = v[j][i][0]; tp[1] = v[j][i][1]; tp[2] = v[j][i][2]; tp[3] = v[j][i][3];
;       }
;     __syncthreads();
; #pragma unroll
;     for (int j = 0; j < 4; ++j) {
;       const int t = t0 + j * gridDim.x;
;       if (t < nt4) {
;         const int kt = t % tk, nt = t / tk;
;         const int nn = tid >> 3, k8 = (tid & 7) * 8;
;         const float* tp = tile + j * TS + k8 * 65 + nn;
;         u32x4 u;
;         u.x = pack2(tp[0 * 65], tp[1 * 65]); u.y = pack2(tp[2 * 65], tp[3 * 65]);
;         u.z = pack2(tp[4 * 65], tp[5 * 65]); u.w = pack2(tp[6 * 65], tp[7 * 65]);
;         *(u32x4*)(dst + (size_t)(nt * 64 + nn) * K + kt * 64 + k8) = u;
.LBB0_217:
	s_or_b64 exec, exec, s[40:41]
	s_add_i32 s53, s52, s42
	s_ashr_i32 s38, s53, 31
	s_lshr_b32 s38, s38, 28
	s_add_i32 s38, s53, s38
	s_and_b32 s39, s38, 0x3fffff0
	s_sub_i32 s44, s53, s39
	s_lshl_b32 s39, s38, 2
	s_andn2_b32 s39, s39, 63
	v_or_b32_e32 v24, s39, v38
	s_cmpk_lt_i32 s53, 0x400
	s_cselect_b64 s[40:41], -1, 0
	v_cmp_gt_i32_e32 vcc, s50, v24
	v_ashrrev_i32_e32 v25, 31, v24
	s_and_b64 s[42:43], s[40:41], vcc
	s_lshl_b32 s38, s44, 6
	v_lshl_add_u64 v[34:35], v[24:25], 2, s[8:9]
	v_mov_b32_e32 v24, 0
	v_mov_b32_e32 v28, 0
	v_mov_b32_e32 v29, 0
	v_mov_b32_e32 v30, 0
	v_mov_b32_e32 v31, 0
	s_and_saveexec_b64 s[44:45], s[42:43]
	s_cbranch_execz .LBB0_220
	v_add_u32_e32 v26, s38, v41
	v_ashrrev_i32_e32 v27, 31, v26
	v_lshlrev_b64 v[28:29], 14, v[26:27]
	v_lshl_add_u64 v[28:29], v[34:35], 0, v[28:29]
	global_load_dwordx4 v[84:87], v[28:29], off
	s_and_b64 vcc, exec, s[4:5]
	s_cbranch_vccnz .LBB0_220
	v_lshl_add_u64 v[26:27], v[26:27], 2, s[22:23]
	global_load_dword v212, v[26:27], off
.LBB0_220:
	s_or_b64 exec, exec, s[44:45]
	v_mov_b32_e32 v25, 0
	v_mov_b32_e32 v26, 0
	v_mov_b32_e32 v27, 0
	s_and_saveexec_b64 s[44:45], s[42:43]
	s_cbranch_execz .LBB0_223
	v_add_u32_e32 v36, s38, v42
	v_ashrrev_i32_e32 v37, 31, v36
	v_lshlrev_b64 v[24:25], 14, v[36:37]
	v_lshl_add_u64 v[24:25], v[34:35], 0, v[24:25]
	global_load_dwordx4 v[88:91], v[24:25], off
	s_and_b64 vcc, exec, s[4:5]
	s_cbranch_vccnz .LBB0_223
	v_lshl_add_u64 v[34:35], v[36:37], 2, s[22:23]
	global_load_dword v214, v[34:35], off
.LBB0_223:
	s_or_b64 exec, exec, s[44:45]
	s_barrier
	s_waitcnt vmcnt(0)
	v_pk_mul_f32 v[6:7], v[62:63], v[200:201] op_sel_hi:[1,0]
	v_pk_mul_f32 v[4:5], v[60:61], v[200:201] op_sel_hi:[1,0]
	v_pk_mul_f32 v[2:3], v[66:67], v[202:203] op_sel_hi:[1,0]
	v_pk_mul_f32 v[0:1], v[64:65], v[202:203] op_sel_hi:[1,0]
	v_pk_mul_f32 v[14:15], v[70:71], v[204:205] op_sel_hi:[1,0]
	v_pk_mul_f32 v[12:13], v[68:69], v[204:205] op_sel_hi:[1,0]
	v_pk_mul_f32 v[10:11], v[74:75], v[206:207] op_sel_hi:[1,0]
	v_pk_mul_f32 v[8:9], v[72:73], v[206:207] op_sel_hi:[1,0]
	v_pk_mul_f32 v[22:23], v[78:79], v[208:209] op_sel_hi:[1,0]
	v_pk_mul_f32 v[20:21], v[76:77], v[208:209] op_sel_hi:[1,0]
	v_pk_mul_f32 v[18:19], v[82:83], v[210:211] op_sel_hi:[1,0]
	v_pk_mul_f32 v[16:17], v[80:81], v[210:211] op_sel_hi:[1,0]
	v_pk_mul_f32 v[30:31], v[86:87], v[212:213] op_sel_hi:[1,0]
	v_pk_mul_f32 v[28:29], v[84:85], v[212:213] op_sel_hi:[1,0]
	v_pk_mul_f32 v[26:27], v[90:91], v[214:215] op_sel_hi:[1,0]
	v_pk_mul_f32 v[24:25], v[88:89], v[214:215] op_sel_hi:[1,0]
	ds_write2_b32 v43, v4, v5 offset1:1
	ds_write2_b32 v43, v6, v7 offset0:2 offset1:3
	ds_write2_b32 v44, v0, v1 offset1:1
	ds_write2_b32 v44, v2, v3 offset0:2 offset1:3
	v_add_u32_e32 v0, 0x4100, v43
	ds_write2_b32 v0, v12, v13 offset1:1
	v_add_u32_e32 v0, 0x4108, v43
	ds_write2_b32 v0, v14, v15 offset1:1
	v_add_u32_e32 v0, 0x4100, v44
	ds_write2_b32 v0, v8, v9 offset1:1
	v_add_u32_e32 v0, 0x4108, v44
	ds_write2_b32 v0, v10, v11 offset1:1
	v_add_u32_e32 v0, 0x8200, v43
	ds_write2_b32 v0, v20, v21 offset1:1
	v_add_u32_e32 v0, 0x8208, v43
	ds_write2_b32 v0, v22, v23 offset1:1
	v_add_u32_e32 v0, 0x8200, v44
	ds_write2_b32 v0, v16, v17 offset1:1
	v_add_u32_e32 v0, 0x8208, v44
	ds_write2_b32 v0, v18, v19 offset1:1
	v_add_u32_e32 v0, 0xc300, v43
	ds_write2_b32 v0, v28, v29 offset1:1
	v_add_u32_e32 v0, 0xc308, v43
	ds_write2_b32 v0, v30, v31 offset1:1
	v_add_u32_e32 v0, 0xc300, v44
	ds_write2_b32 v0, v24, v25 offset1:1
	v_add_u32_e32 v0, 0xc308, v44
	ds_write2_b32 v0, v26, v27 offset1:1
	s_waitcnt lgkmcnt(0)
	s_barrier
	ds_read2_b32 v[0:1], v40 offset1:65
	ds_read2_b32 v[2:3], v40 offset0:130 offset1:195
	v_add_u32_e32 v6, 0x400, v40
	ds_read2_b32 v[4:5], v6 offset0:4 offset1:69
	ds_read2_b32 v[6:7], v6 offset0:134 offset1:199
	s_andn2_b64 vcc, exec, s[30:31]
	s_waitcnt lgkmcnt(3)
	v_cvt_pk_bf16_f32 v0, v0, v1
	s_waitcnt lgkmcnt(2)
	v_cvt_pk_bf16_f32 v1, v2, v3
	s_waitcnt lgkmcnt(1)
	v_cvt_pk_bf16_f32 v2, v4, v5
	v_add_u32_e32 v4, s29, v39
	v_ashrrev_i32_e32 v5, 31, v4
	v_lshlrev_b64 v[4:5], 11, v[4:5]
	v_lshl_add_u64 v[4:5], s[20:21], 0, v[4:5]
	s_ashr_i32 s29, s28, 31
	v_lshl_add_u64 v[4:5], s[28:29], 1, v[4:5]
	s_waitcnt lgkmcnt(0)
	v_cvt_pk_bf16_f32 v3, v6, v7
	v_lshl_add_u64 v[4:5], v[4:5], 0, v[32:33]
	global_store_dwordx4 v[4:5], v[0:3], off
	s_cbranch_vccz .LBB0_226
	s_andn2_b64 vcc, exec, s[36:37]
	s_cbranch_vccz .LBB0_227
